# copyshare4: K/V-projection CUs keep 2 w_in copy rounds; chain CU c copies rounds 6-7 of virtual CUs 2c,2c+1 before its w_out share
# baseline (speedup 1.0000x reference)
; #define LAS __attribute__((address_space(3)))
; #define P (*({ CParams* q_ = kp; asm volatile("" : "+s"(q_)); q_; }))
; DI void p0_matrix(const float* W, const float* gain, int K, int N, bf16_t* WT, LAS float* scr, int nitems, int gw, int NGW, int lane) {
;     for (int it = gw; it < nitems; it += 4 * NGW) {
;         const int it2 = it + NGW, it3 = it + 2 * NGW, it4 = it + 3 * NGW; const bool h2 = it2 < nitems, h3 = it3 < nitems, h4 = it4 < nitems;
; __global__ void __launch_bounds__(NTHREADS, 2) fwd_megakernel(Params P_) {
;     ...
;         if (bx >= 160) { int t2 = threadIdx.x; asm volatile("" : "+v"(t2)); const int w2 = __builtin_amdgcn_readfirstlane(t2 >> 6);
;             convert_weights(P, 1, lds, (bx - 160) * NWAVES + w2, 96 * NWAVES, t2 & 63, w2, l == 0 ? 5 : 2); }
.Lcopy_cls_lo:
	s_cmpk_lt_i32 s69, 0x20
	s_cbranch_scc0 .Lcopy_cls_mid
	s_and_b32 s1, s1, 3
	s_movk_i32 s98, 0x4800
	s_mov_b32 s101, 0
	s_branch .Lcopy_cls_done

; #define LAS __attribute__((address_space(3)))
; #define P (*({ CParams* q_ = kp; asm volatile("" : "+s"(q_)); q_; }))
; DI void p0_matrix(const float* W, const float* gain, int K, int N, bf16_t* WT, LAS float* scr, int nitems, int gw, int NGW, int lane) {
;     for (int it = gw; it < nitems; it += 4 * NGW) {
;         const int it2 = it + NGW, it3 = it + 2 * NGW, it4 = it + 3 * NGW; const bool h2 = it2 < nitems, h3 = it3 < nitems, h4 = it4 < nitems;
; __global__ void __launch_bounds__(NTHREADS, 2) fwd_megakernel(Params P_) {
;     ...
;         if (bx >= 160) { int t2 = threadIdx.x; asm volatile("" : "+v"(t2)); const int w2 = __builtin_amdgcn_readfirstlane(t2 >> 6);
;             convert_weights(P, 1, lds, (bx - 160) * NWAVES + w2, 96 * NWAVES, t2 & 63, w2, l == 0 ? 5 : 2); }
.Lcopy_cls_hi:
	s_movk_i32 s98, 0x3000
	s_movk_i32 s99, 0x3c00
